# h3ABdma
# speedup vs baseline: 1.0057x; 1.0057x over previous
.LBB0_214:
	s_andn2_b64 vcc, exec, s[34:35]
	s_cbranch_vccnz .LBB0_216
	s_ashr_i32 s13, s12, 31
	s_mul_i32 s34, s12, 0xc00
	s_mul_hi_i32 s35, s12, 0xc00
	s_add_u32 s34, s8, s34
	s_addc_u32 s35, s9, s35
	v_readfirstlane_b32 s45, v197
	s_xor_b32 m0, s42, 1
	s_mulk_i32 m0, 0x6000
	s_add_i32 m0, m0, s45
	s_add_i32 m0, m0, 0x8000
	s_nop 0
	global_load_lds_dwordx4 v0, s[34:35]
	s_add_i32 m0, m0, 0x2000
	s_nop 0
	global_load_lds_dwordx4 v150, s[34:35]
	s_add_i32 m0, m0, 0x2000
	s_nop 0
	global_load_lds_dwordx4 v152, s[34:35]
	s_lshl_b64 s[34:35], s[12:13], 11
	s_add_u32 s34, s10, s34
	s_addc_u32 s35, s11, s35
	s_lshl_b32 s13, s42, 14
	s_xor_b32 s13, s13, 0x4000
	s_add_i32 m0, s13, s45
	s_nop 0
	global_load_lds_dwordx4 v154, s[34:35]
	s_add_i32 m0, m0, 0x2000
	s_nop 0
	global_load_lds_dwordx4 v156, s[34:35]

.LBB0_231:
	s_andn2_b64 vcc, exec, s[12:13]
	s_cbranch_vccnz .LBB0_233
	s_mul_i32 s42, s2, 0x5e00
	s_mul_hi_i32 s35, s2, 0x5e00
	s_add_u32 s12, s8, s42
	s_addc_u32 s13, s9, s35
	v_readfirstlane_b32 s45, v150
	s_lshl_b32 m0, s34, 14
	s_xor_b32 m0, m0, 0x4000
	s_add_i32 s45, s45, m0
	s_add_i32 m0, s45, 0x8000
	s_nop 0
	global_load_lds_dwordx4 v0, s[12:13]
	s_add_i32 m0, s45, 0xa000
	s_nop 0
	global_load_lds_dwordx4 v130, s[12:13]
	s_add_u32 s12, s10, s42
	s_addc_u32 s13, s11, s35
	s_mov_b32 m0, s45
	s_nop 0
	global_load_lds_dwordx4 v132, s[12:13]
	s_add_i32 m0, s45, 0x2000
	s_nop 0
	global_load_lds_dwordx4 v134, s[12:13]
